# layer-0 gatenorm-phase weight conversion segment dealt over all 256 workgroups (first idle block 32 -> 0)
# baseline (speedup 1.0000x reference)
.LBB0_1142:
	s_or_b64 exec, exec, s[8:9]
	v_readlane_b32 s0, v244, 13
	v_readlane_b32 s1, v244, 14
	s_andn2_b64 vcc, exec, s[0:1]
	s_cbranch_vccnz .LBB0_1148
	v_mov_b32_e32 v0, v180
	v_readlane_b32 s0, v246, 0
	s_cmp_lt_i32 s0, 0
	s_cbranch_scc1 .LBB0_1148
	v_ashrrev_i32_e32 v1, 6, v0
	v_lshl_add_u32 v2, s0, 3, v1
	v_add_u32_e32 v2, 0, v2
	s_movk_i32 s0, 0x1c20
	v_cmp_gt_u32_e32 vcc, s0, v2
	s_and_saveexec_b64 s[0:1], vcc
	s_mov_b32 s6, 0x3840000
	s_mov_b32 s7, 0x1d00000
	s_movk_i32 s14, 0xe1
	s_cbranch_execz .LBB0_1147
	v_add_u32_e32 v9, 0x1c20, v2
	v_bfe_u32 v8, v0, 5, 1
	v_and_b32_e32 v2, 31, v0
	v_bfe_u32 v10, v0, 3, 3
	v_lshlrev_b32_e32 v0, 3, v0
	v_lshl_add_u32 v1, v1, 14, 0
	v_and_b32_e32 v0, 56, v0
	s_add_u32 s8, s26, 0x100000
	v_lshl_add_u32 v3, v2, 2, v1
	v_mul_u32_u24_e32 v4, 0x84, v8
	v_mul_u32_u24_e32 v5, 0x84, v0
	v_lshlrev_b32_e32 v6, 2, v10
	s_addc_u32 s9, s27, 0
	v_add3_u32 v11, v1, v5, v6
	v_or_b32_e32 v12, 8, v10
	v_or_b32_e32 v13, 24, v10
	v_or_b32_e32 v14, 16, v10
	s_mov_b64 s[12:13], 0
	v_lshlrev_b32_e32 v144, 2, v2
	v_add_u32_e32 v15, v3, v4
	v_lshlrev_b32_e32 v0, 1, v0
.LBB0_1146:
	v_mul_hi_u32 v1, v9, s88
	v_lshrrev_b32_e32 v1, 12, v1
	v_mul_i32_i24_e32 v2, 0xffffe3e0, v1
	v_add_u32_e32 v6, v2, v9
	v_mov_b64_e32 v[2:3], s[28:29]
	v_mad_u64_u32 v[16:17], s[4:5], v1, s6, v[2:3]
	v_mov_b64_e32 v[2:3], s[8:9]
	v_mad_u64_u32 v[4:5], s[4:5], v1, s7, v[2:3]
	v_mul_hi_i32 v1, v6, s88
	v_add_u32_e32 v1, v1, v6
	v_lshrrev_b32_e32 v2, 31, v1
	v_ashrrev_i32_e32 v1, 7, v1
	v_add_u32_e32 v1, v1, v2
	v_mul_lo_u32 v2, v1, s14
	v_sub_u32_e32 v2, v6, v2
	v_lshlrev_b32_e32 v2, 5, v2
	v_ashrrev_i32_e32 v3, 31, v2
	v_lshlrev_b32_e32 v6, 6, v1
	v_lshl_add_u64 v[16:17], v[2:3], 2, v[16:17]
	v_or_b32_e32 v44, v6, v8
	v_lshl_add_u64 v[40:41], v[16:17], 0, v[144:145]
	v_mad_i64_i32 v[16:17], s[4:5], v44, s50, v[40:41]
	v_or_b32_e32 v1, 2, v44
	flat_load_dword v45, v[16:17]
	v_mad_i64_i32 v[16:17], s[4:5], v1, s50, v[40:41]
	v_or_b32_e32 v1, 4, v44
	flat_load_dword v46, v[16:17]
	v_mad_i64_i32 v[16:17], s[4:5], v1, s50, v[40:41]
	v_or_b32_e32 v1, 6, v44
	flat_load_dword v47, v[16:17]
	v_mad_i64_i32 v[16:17], s[4:5], v1, s50, v[40:41]
	v_or_b32_e32 v1, 8, v44
	flat_load_dword v48, v[16:17]
	v_mad_i64_i32 v[16:17], s[4:5], v1, s50, v[40:41]
	v_or_b32_e32 v3, 10, v44
	flat_load_dword v1, v[16:17]
	v_mad_i64_i32 v[16:17], s[4:5], v3, s50, v[40:41]
	v_or_b32_e32 v3, 12, v44
	v_mad_i64_i32 v[18:19], s[4:5], v3, s50, v[40:41]
	v_or_b32_e32 v3, 14, v44
	flat_load_dword v16, v[16:17]
	v_or_b32_e32 v7, 18, v44
	flat_load_dword v20, v[18:19]
	v_mad_i64_i32 v[18:19], s[4:5], v3, s50, v[40:41]
	v_or_b32_e32 v3, 16, v44
	flat_load_dword v28, v[18:19]
	v_mad_i64_i32 v[18:19], s[4:5], v3, s50, v[40:41]
	flat_load_dword v3, v[18:19]
	v_mad_i64_i32 v[18:19], s[4:5], v7, s50, v[40:41]
	v_or_b32_e32 v7, 20, v44
	v_mad_i64_i32 v[22:23], s[4:5], v7, s50, v[40:41]
	v_or_b32_e32 v7, 22, v44
	v_mad_i64_i32 v[24:25], s[4:5], v7, s50, v[40:41]
	v_or_b32_e32 v7, 24, v44
	flat_load_dword v18, v[18:19]
	v_or_b32_e32 v17, 26, v44
	flat_load_dword v23, v[22:23]
	v_or_b32_e32 v37, 60, v44
	flat_load_dword v31, v[24:25]
	v_mad_i64_i32 v[24:25], s[4:5], v7, s50, v[40:41]
	flat_load_dword v7, v[24:25]
	v_mad_i64_i32 v[24:25], s[4:5], v17, s50, v[40:41]
	v_or_b32_e32 v17, 28, v44
	flat_load_dword v21, v[24:25]
	v_mad_i64_i32 v[24:25], s[4:5], v17, s50, v[40:41]
	v_or_b32_e32 v17, 30, v44
	flat_load_dword v26, v[24:25]
	v_mad_i64_i32 v[24:25], s[4:5], v17, s50, v[40:41]
	v_or_b32_e32 v17, 32, v44
	flat_load_dword v34, v[24:25]
	v_mad_i64_i32 v[24:25], s[4:5], v17, s50, v[40:41]
	v_or_b32_e32 v19, 34, v44
	flat_load_dword v17, v[24:25]
	v_mad_i64_i32 v[24:25], s[4:5], v19, s50, v[40:41]
	v_or_b32_e32 v19, 36, v44
	v_mad_i64_i32 v[32:33], s[4:5], v19, s50, v[40:41]
	v_or_b32_e32 v19, 38, v44
	flat_load_dword v24, v[24:25]
	v_or_b32_e32 v22, 42, v44
	flat_load_dword v29, v[32:33]
	v_mad_i64_i32 v[32:33], s[4:5], v19, s50, v[40:41]
	v_or_b32_e32 v19, 40, v44
	flat_load_dword v36, v[32:33]
	v_mad_i64_i32 v[32:33], s[4:5], v19, s50, v[40:41]
	flat_load_dword v19, v[32:33]
	v_mad_i64_i32 v[32:33], s[4:5], v22, s50, v[40:41]
	v_or_b32_e32 v22, 44, v44
	flat_load_dword v27, v[32:33]
	v_mad_i64_i32 v[32:33], s[4:5], v22, s50, v[40:41]
	v_or_b32_e32 v22, 46, v44
	v_mad_i64_i32 v[38:39], s[4:5], v22, s50, v[40:41]
	v_or_b32_e32 v22, 48, v44
	v_mad_i64_i32 v[42:43], s[4:5], v22, s50, v[40:41]
	v_or_b32_e32 v25, 50, v44
	flat_load_dword v32, v[32:33]
	s_movk_i32 s2, 0x303f
	flat_load_dword v38, v[38:39]
	v_cmp_lt_i32_e32 vcc, s2, v9
	flat_load_dword v22, v[42:43]
	v_mad_i64_i32 v[42:43], s[4:5], v25, s50, v[40:41]
	v_or_b32_e32 v25, 52, v44
	flat_load_dword v30, v[42:43]
	v_mad_i64_i32 v[42:43], s[4:5], v25, s50, v[40:41]
	v_or_b32_e32 v25, 54, v44
	flat_load_dword v35, v[42:43]
	v_mad_i64_i32 v[42:43], s[4:5], v25, s50, v[40:41]
	v_or_b32_e32 v25, 56, v44
	flat_load_dword v39, v[42:43]
	v_mad_i64_i32 v[42:43], s[4:5], v25, s50, v[40:41]
	v_or_b32_e32 v33, 58, v44
	flat_load_dword v25, v[42:43]
	v_mad_i64_i32 v[42:43], s[4:5], v33, s50, v[40:41]
	flat_load_dword v33, v[42:43]
	v_mad_i64_i32 v[42:43], s[4:5], v37, s50, v[40:41]
	flat_load_dword v37, v[42:43]
	v_or_b32_e32 v42, 62, v44
	v_mad_i64_i32 v[40:41], s[4:5], v42, s50, v[40:41]
	flat_load_dword v40, v[40:41]
	v_add_u32_e32 v41, 0x400, v15
	s_waitcnt vmcnt(0) lgkmcnt(0)
	ds_write2_b32 v15, v45, v46 offset1:66
	ds_write2_b32 v15, v47, v48 offset0:132 offset1:198
	ds_write2_b32 v41, v1, v16 offset0:8 offset1:74
	ds_write2_b32 v41, v20, v28 offset0:140 offset1:206
	v_add_u32_e32 v1, 0x800, v15
	ds_write2_b32 v1, v3, v18 offset0:16 offset1:82
	ds_write2_b32 v1, v23, v31 offset0:148 offset1:214
	v_add_u32_e32 v1, 0xc00, v15
	ds_write2_b32 v1, v7, v21 offset0:24 offset1:90
	ds_write2_b32 v1, v26, v34 offset0:156 offset1:222
	v_add_u32_e32 v1, 0x1000, v15
	ds_write2_b32 v1, v17, v24 offset0:32 offset1:98
	ds_write2_b32 v1, v29, v36 offset0:164 offset1:230
	v_add_u32_e32 v1, 0x1400, v15
	ds_write2_b32 v1, v19, v27 offset0:40 offset1:106
	ds_write2_b32 v1, v32, v38 offset0:172 offset1:238
	v_add_u32_e32 v1, 0x1800, v15
	ds_write2_b32 v1, v22, v30 offset0:48 offset1:114
	ds_write2_b32 v1, v35, v39 offset0:180 offset1:246
	v_add_u32_e32 v1, 0x1c00, v15
	ds_write2_b32 v1, v25, v33 offset0:56 offset1:122
	ds_write2_b32 v1, v37, v40 offset0:188 offset1:254
	v_ashrrev_i32_e32 v7, 31, v6
	s_waitcnt lgkmcnt(0)
	v_lshl_add_u64 v[4:5], v[6:7], 1, v[4:5]
	v_mov_b32_e32 v1, v145
	v_lshl_add_u64 v[16:17], v[4:5], 0, v[0:1]
	ds_read_b32 v1, v11
	ds_read_b32 v3, v11 offset:132
	v_or_b32_e32 v18, v2, v10
	v_ashrrev_i32_e32 v19, 31, v18
	v_lshlrev_b64 v[18:19], 12, v[18:19]
	s_waitcnt lgkmcnt(1)
	v_add_u32_e32 v1, 0x8000, v1
	s_waitcnt lgkmcnt(0)
	v_add_u32_e32 v3, 0x8000, v3
	v_perm_b32 v4, v3, v1, s81
	ds_read_b32 v1, v11 offset:264
	ds_read_b32 v3, v11 offset:396
	v_lshl_add_u64 v[18:19], v[16:17], 0, v[18:19]
	s_or_b64 s[12:13], vcc, s[12:13]
	s_waitcnt lgkmcnt(1)
	v_add_u32_e32 v1, 0x8000, v1
	s_waitcnt lgkmcnt(0)
	v_add_u32_e32 v3, 0x8000, v3
	v_perm_b32 v5, v3, v1, s81
	ds_read_b32 v1, v11 offset:528
	ds_read_b32 v3, v11 offset:660
	s_waitcnt lgkmcnt(1)
	v_add_u32_e32 v1, 0x8000, v1
	s_waitcnt lgkmcnt(0)
	v_add_u32_e32 v3, 0x8000, v3
	v_perm_b32 v6, v3, v1, s81
	ds_read_b32 v1, v11 offset:792
	ds_read_b32 v3, v11 offset:924
	s_waitcnt lgkmcnt(1)
	v_add_u32_e32 v1, 0x8000, v1
	s_waitcnt lgkmcnt(0)
	v_add_u32_e32 v3, 0x8000, v3
	v_perm_b32 v7, v3, v1, s81
	flat_store_dwordx4 v[18:19], v[4:7]
	ds_read_b32 v1, v11 offset:32
	ds_read_b32 v3, v11 offset:164
	v_or_b32_e32 v18, v2, v12
	v_ashrrev_i32_e32 v19, 31, v18
	v_lshlrev_b64 v[18:19], 12, v[18:19]
	s_waitcnt lgkmcnt(0)
	v_add_u32_e32 v1, 0x8000, v1
	v_add_u32_e32 v3, 0x8000, v3
	v_perm_b32 v4, v3, v1, s81
	ds_read_b32 v1, v11 offset:296
	ds_read_b32 v3, v11 offset:428
	v_lshl_add_u64 v[18:19], v[16:17], 0, v[18:19]
	s_waitcnt lgkmcnt(0)
	v_add_u32_e32 v1, 0x8000, v1
	v_add_u32_e32 v3, 0x8000, v3
	v_perm_b32 v5, v3, v1, s81
	ds_read_b32 v1, v11 offset:560
	ds_read_b32 v3, v11 offset:692
	s_waitcnt lgkmcnt(0)
	v_add_u32_e32 v1, 0x8000, v1
	v_add_u32_e32 v3, 0x8000, v3
	v_perm_b32 v6, v3, v1, s81
	ds_read_b32 v1, v11 offset:824
	ds_read_b32 v3, v11 offset:956
	s_waitcnt lgkmcnt(0)
	v_add_u32_e32 v1, 0x8000, v1
	v_add_u32_e32 v3, 0x8000, v3
	v_perm_b32 v7, v3, v1, s81
	flat_store_dwordx4 v[18:19], v[4:7]
	ds_read_b32 v1, v11 offset:64
	ds_read_b32 v3, v11 offset:196
	v_or_b32_e32 v18, v2, v14
	v_ashrrev_i32_e32 v19, 31, v18
	v_lshlrev_b64 v[18:19], 12, v[18:19]
	s_waitcnt lgkmcnt(0)
	v_add_u32_e32 v1, 0x8000, v1
	v_add_u32_e32 v3, 0x8000, v3
	v_perm_b32 v4, v3, v1, s81
	ds_read_b32 v1, v11 offset:328
	ds_read_b32 v3, v11 offset:460
	v_lshl_add_u64 v[18:19], v[16:17], 0, v[18:19]
	v_or_b32_e32 v2, v2, v13
	s_waitcnt lgkmcnt(0)
	v_add_u32_e32 v1, 0x8000, v1
	v_add_u32_e32 v3, 0x8000, v3
	v_perm_b32 v5, v3, v1, s81
	ds_read_b32 v1, v11 offset:592
	ds_read_b32 v3, v11 offset:724
	s_waitcnt lgkmcnt(0)
	v_add_u32_e32 v1, 0x8000, v1
	v_add_u32_e32 v3, 0x8000, v3
	v_perm_b32 v6, v3, v1, s81
	ds_read_b32 v1, v11 offset:856
	ds_read_b32 v3, v11 offset:988
	s_waitcnt lgkmcnt(0)
	v_add_u32_e32 v1, 0x8000, v1
	v_add_u32_e32 v3, 0x8000, v3
	v_perm_b32 v7, v3, v1, s81
	flat_store_dwordx4 v[18:19], v[4:7]
	ds_read_b32 v1, v11 offset:96
	ds_read_b32 v3, v11 offset:228
	s_waitcnt lgkmcnt(0)
	v_add_u32_e32 v1, 0x8000, v1
	v_add_u32_e32 v3, 0x8000, v3
	v_perm_b32 v4, v3, v1, s81
	ds_read_b32 v1, v11 offset:360
	ds_read_b32 v3, v11 offset:492
	s_waitcnt lgkmcnt(0)
	v_add_u32_e32 v1, 0x8000, v1
	v_add_u32_e32 v3, 0x8000, v3
	v_perm_b32 v5, v3, v1, s81
	ds_read_b32 v1, v11 offset:624
	ds_read_b32 v3, v11 offset:756
	s_waitcnt lgkmcnt(0)
	v_add_u32_e32 v1, 0x8000, v1
	v_add_u32_e32 v3, 0x8000, v3
	v_perm_b32 v6, v3, v1, s81
	ds_read_b32 v1, v11 offset:888
	ds_read_b32 v3, v11 offset:1020
	s_waitcnt lgkmcnt(0)
	v_add_u32_e32 v1, 0x8000, v1
	v_add_u32_e32 v3, 0x8000, v3
	v_perm_b32 v7, v3, v1, s81
	v_ashrrev_i32_e32 v3, 31, v2
	v_lshlrev_b64 v[2:3], 12, v[2:3]
	v_lshl_add_u64 v[2:3], v[16:17], 0, v[2:3]
	flat_store_dwordx4 v[2:3], v[4:7]
	s_waitcnt lgkmcnt(0)
	v_add_u32_e32 v1, 0x800, v9
	v_mov_b32_e32 v9, v1
	s_andn2_b64 exec, exec, s[12:13]
	s_cbranch_execnz .LBB0_1146
